# e56 + third out_w/glu_w transpose items of workgroups vcu>=134 moved to the S5-table workgroups (one item each at the end of their P1)
# speedup vs baseline: 1.0024x; 1.0024x over previous
; #define LAS __attribute__((address_space(3)))
; __device__ __forceinline__ f32x4 ld_nt(const float* p) { return __builtin_nontemporal_load((const f32x4*)p); }
; #define SUB(i, ...) do { if (PROBE_PH == phk && PROBE_SUB == (i)) { __syncthreads(); tp0 = __builtin_amdgcn_s_memrealtime(); } __VA_ARGS__ if (PROBE_PH == phk && PROBE_SUB == (i)) { asm volatile("s_waitcnt vmcnt(0)" ::: "memory"); __syncthreads(); tp1 = __builtin_amdgcn_s_memrealtime(); } } while (0)
; __device__ __forceinline__ void transpose_item(const float* W, int K, int pitch, int ncols, f16* WT, LAS float* scr, int item, int lane) {
;     const int nblk = ncols / 32, kb = item / nblk, nb = item % nblk, k0 = 64 * kb, n0 = 32 * nb;
;     const int kr = lane >> 3, nq = (lane & 7) * 4;
;     f32x4 v[8];
; #pragma unroll
;     for (int i = 0; i < 8; ++i) v[i] = ld_nt(W + (size_t)(k0 + kr + 8 * i) * pitch + n0 + nq);
;     __builtin_amdgcn_sched_barrier(0);
; #pragma unroll
;     for (int i = 0; i < 8; ++i) { LAS float* sp = scr + (kr + 8 * i) * 33 + nq; sp[0] = v[i][0]; sp[1] = v[i][1]; sp[2] = v[i][2]; sp[3] = v[i][3]; }
;     asm volatile("s_waitcnt lgkmcnt(0)" ::: "memory");
;     const int c = lane & 7;
; #pragma unroll
;     for (int j = 0; j < 4; ++j) { const int n = (lane >> 3) + 8 * j; const LAS float* sp = scr + (8 * c) * 33 + n;
;         u32x4 o; o.x = pk_f16(sp[0 * 33], sp[1 * 33]); o.y = pk_f16(sp[2 * 33], sp[3 * 33]); o.z = pk_f16(sp[4 * 33], sp[5 * 33]); o.w = pk_f16(sp[6 * 33], sp[7 * 33]);
;         *(u32x4*)(WT + (size_t)(n0 + n) * K + k0 + 8 * c) = o; }
;     asm volatile("s_waitcnt lgkmcnt(0)" ::: "memory");
; }
; __global__ void __launch_bounds__(NTHREADS, 2) mk_fwd(Args a) {
;     ...
;         SUB(2, if (vcu < 128) transpose_dispatch((320 + vcu) * 8 + wave, a.in[7], a.in[20], a.in[18], a.in[8], a.ws, scr, lane);
;                else { const int b2 = vcu - 128;
;                    for (int it = 448 + 3 * b2; it < 448 + 3 * b2 + 3; ++it) transpose_dispatch(it * 8 + wave, a.in[7], a.in[20], a.in[18], a.in[8], a.ws, scr, lane);
;                    if (b2 < 16) transpose_dispatch((832 + b2) * 8 + wave, a.in[7], a.in[20], a.in[18], a.in[8], a.ws, scr, lane); } );
.Lp1_tr_setup:
	v_readlane_b32 s56, v254, 2
	v_and_b32_e32 v5, 7, v0
	v_readlane_b32 s70, v254, 16
	v_readlane_b32 s71, v254, 17
	v_mov_b32_e32 v7, 0
	s_add_u32 s10, s50, 0x1c00000
	v_lshlrev_b32_e32 v6, 4, v5
	s_mov_b64 s[22:23], s[70:71]
	s_addc_u32 s11, s51, 0
	v_lshl_add_u64 v[16:17], s[22:23], 0, v[6:7]
	s_mov_b64 s[8:9], 0x1000
	v_lshrrev_b32_e32 v24, 3, v212
	s_add_u32 s2, s50, 0x1400000
	v_lshl_add_u64 v[16:17], v[16:17], 0, s[8:9]
	v_lshl_add_u64 v[18:19], s[50:51], 0, v[6:7]
	s_mov_b64 s[8:9], 0x800000
	v_lshlrev_b32_e32 v4, 2, v5
	v_lshlrev_b32_e32 v2, 3, v5
	v_mul_u32_u24_e32 v5, 0x420, v5
	v_lshlrev_b32_e32 v12, 2, v24
	s_addc_u32 s3, s51, 0
	v_lshl_add_u64 v[18:19], v[18:19], 0, s[8:9]
	s_mul_i32 s9, s81, 24
	v_lshl_add_u64 v[8:9], s[40:41], 0, v[6:7]
	v_add_u32_e32 v26, s28, v6
	v_mul_u32_u24_e32 v27, 0x84, v24
	v_lshl_add_u64 v[10:11], s[10:11], 0, v[6:7]
	v_add3_u32 v5, s28, v5, v12
	v_lshl_add_u64 v[12:13], s[44:45], 0, v[6:7]
	v_lshl_add_u64 v[14:15], s[2:3], 0, v[6:7]
	v_lshlrev_b32_e32 v6, 6, v212
	s_add_i32 s12, s53, s9
	s_mul_i32 s7, s20, 3
	v_lshl_add_u64 v[20:21], s[22:23], 0, v[6:7]
	v_lshlrev_b32_e32 v6, 5, v212
	s_mul_i32 s8, s81, 3
	s_add_i32 s9, s12, 0xf380
	s_lshl_b32 s14, s12, 5
	s_addk_i32 s12, 0x180
	v_add_u32_e32 v26, v26, v27
	v_or_b32_e32 v25, 8, v24
	v_or_b32_e32 v3, 16, v24
	v_or_b32_e32 v1, 24, v24
	v_lshl_add_u64 v[22:23], s[4:5], 0, v[6:7]
	s_addk_i32 s7, 0x1c2
	s_add_i32 s8, s8, 63
	s_movk_i32 s18, 0x4000
	s_add_i32 s19, s14, 0x4000
	s_lshl_b32 s14, s12, 12
	s_lshl_b32 s12, s12, 14
	v_add_u32_e32 v27, 0x420, v26
	v_add_u32_e32 v28, 0x428, v26
	v_add_u32_e32 v29, 0x840, v26
	v_add_u32_e32 v30, 0x848, v26
	v_add_u32_e32 v31, 0xc60, v26
	v_add_u32_e32 v32, 0xc68, v26
	v_add_u32_e32 v33, 0x1080, v26
	v_add_u32_e32 v34, 0x1088, v26
	v_add_u32_e32 v35, 0x14a0, v26
	v_add_u32_e32 v36, 0x14a8, v26
	v_add_u32_e32 v37, 0x18c0, v26
	v_add_u32_e32 v38, 0x18c8, v26
	v_add_u32_e32 v39, 0x1ce0, v26
	v_add_u32_e32 v40, 0x1ce8, v26
	s_mov_b32 s29, 0x20000
	s_mov_b32 s30, 0x40000
	s_mov_b32 s31, 0x60000
	s_mov_b32 s33, 0x80000
	s_mov_b32 s34, 0xa0000
	s_mov_b32 s35, 0xc0000
	s_mov_b32 s36, 0xe0000
	s_mov_b64 s[22:23], 0x4000
	s_mov_b64 s[24:25], 0x8000
	s_mov_b32 s37, 0x8000
	s_mov_b64 s[26:27], 0xc000
	s_mov_b32 s54, 0xc000
	s_movk_i32 s55, 0x1000
	v_readlane_b32 s57, v254, 3
	v_readlane_b32 s58, v254, 4
	v_readlane_b32 s59, v254, 5
	v_readlane_b32 s60, v254, 6
	v_readlane_b32 s61, v254, 7
	v_readlane_b32 s62, v254, 8
	v_readlane_b32 s63, v254, 9
	v_readlane_b32 s64, v254, 10
	v_readlane_b32 s65, v254, 11
	v_readlane_b32 s66, v254, 12
	v_readlane_b32 s67, v254, 13
	v_readlane_b32 s68, v254, 14
	v_readlane_b32 s69, v254, 15
	s_cmp_eq_u32 s99, 1
	s_cbranch_scc1 .Lp3_tr_two
	s_cmpk_lt_i32 s81, 0x86
	s_cbranch_scc1 .LBB0_187
	s_branch .LBB0_203

; #define LAS __attribute__((address_space(3)))
; __device__ __forceinline__ f32x4 ld_nt(const float* p) { return __builtin_nontemporal_load((const f32x4*)p); }
; #define SUB(i, ...) do { if (PROBE_PH == phk && PROBE_SUB == (i)) { __syncthreads(); tp0 = __builtin_amdgcn_s_memrealtime(); } __VA_ARGS__ if (PROBE_PH == phk && PROBE_SUB == (i)) { asm volatile("s_waitcnt vmcnt(0)" ::: "memory"); __syncthreads(); tp1 = __builtin_amdgcn_s_memrealtime(); } } while (0)
; __device__ __forceinline__ void transpose_item(const float* W, int K, int pitch, int ncols, f16* WT, LAS float* scr, int item, int lane) {
;     const int nblk = ncols / 32, kb = item / nblk, nb = item % nblk, k0 = 64 * kb, n0 = 32 * nb;
;     const int kr = lane >> 3, nq = (lane & 7) * 4;
;     f32x4 v[8];
; #pragma unroll
;     for (int i = 0; i < 8; ++i) v[i] = ld_nt(W + (size_t)(k0 + kr + 8 * i) * pitch + n0 + nq);
;     __builtin_amdgcn_sched_barrier(0);
; #pragma unroll
;     for (int i = 0; i < 8; ++i) { LAS float* sp = scr + (kr + 8 * i) * 33 + nq; sp[0] = v[i][0]; sp[1] = v[i][1]; sp[2] = v[i][2]; sp[3] = v[i][3]; }
;     asm volatile("s_waitcnt lgkmcnt(0)" ::: "memory");
;     const int c = lane & 7;
; #pragma unroll
;     for (int j = 0; j < 4; ++j) { const int n = (lane >> 3) + 8 * j; const LAS float* sp = scr + (8 * c) * 33 + n;
;         u32x4 o; o.x = pk_f16(sp[0 * 33], sp[1 * 33]); o.y = pk_f16(sp[2 * 33], sp[3 * 33]); o.z = pk_f16(sp[4 * 33], sp[5 * 33]); o.w = pk_f16(sp[6 * 33], sp[7 * 33]);
;         *(u32x4*)(WT + (size_t)(n0 + n) * K + k0 + 8 * c) = o; }
;     asm volatile("s_waitcnt lgkmcnt(0)" ::: "memory");
; }
; __global__ void __launch_bounds__(NTHREADS, 2) mk_fwd(Args a) {
;     ...
;         SUB(2, if (vcu < 128) transpose_dispatch((320 + vcu) * 8 + wave, a.in[7], a.in[20], a.in[18], a.in[8], a.ws, scr, lane);
.LBB0_230:
	s_cmp_lg_u32 s100, 0
	s_cbranch_scc1 .Lp1_stub_old
	s_cmpk_gt_i32 s81, 0x79
	s_cbranch_scc1 .Lp1_stub_old
	s_mov_b32 s100, 4
	s_mul_i32 s6, s81, 3
	s_addk_i32 s6, 0x94
	s_lshl_b32 s6, s6, 3
	s_add_i32 s6, s6, s53
	s_add_u32 s0, s50, 0x2000000
	s_addc_u32 s1, s51, 0
	s_add_u32 s4, s50, 0x13600000
	s_addc_u32 s5, s51, 0
	s_mul_i32 s28, s53, 0x2100
	s_mov_b32 s13, 0
	s_mov_b64 s[2:3], -1
	s_branch .LBB0_213
